# v82 + code placement: 4-byte pads so that all nine GEMM K-loop heads sit at byte offset 4 mod 8 (retention / attention loop placement unchanged)
# speedup vs baseline: 1.0029x; 1.0029x over previous
.LBB0_647:
	s_add_u32 s55, s16, 0x100
	v_mov_b32_e32 v0, 0
	s_addc_u32 s56, s17, 0
	s_mov_b32 s57, -2
	v_mov_b32_e32 v1, v0
	v_mov_b32_e32 v2, v0
	v_mov_b32_e32 v3, v0
	v_mov_b32_e32 v4, v0
	v_mov_b32_e32 v5, v0
	v_mov_b32_e32 v6, v0
	v_mov_b32_e32 v7, v0
	v_mov_b32_e32 v16, v0
	v_mov_b32_e32 v17, v0
	v_mov_b32_e32 v18, v0
	v_mov_b32_e32 v19, v0
	v_mov_b32_e32 v20, v0
	v_mov_b32_e32 v21, v0
	v_mov_b32_e32 v22, v0
	v_mov_b32_e32 v23, v0
	v_mov_b32_e32 v32, v0
	v_mov_b32_e32 v33, v0
	v_mov_b32_e32 v34, v0
	v_mov_b32_e32 v35, v0
	v_mov_b32_e32 v36, v0
	v_mov_b32_e32 v37, v0
	v_mov_b32_e32 v38, v0
	v_mov_b32_e32 v39, v0
	v_mov_b32_e32 v48, v0
	v_mov_b32_e32 v49, v0
	v_mov_b32_e32 v50, v0
	v_mov_b32_e32 v51, v0
	v_mov_b32_e32 v52, v0
	v_mov_b32_e32 v53, v0
	v_mov_b32_e32 v54, v0
	v_mov_b32_e32 v55, v0
	v_mov_b32_e32 v8, v0
	v_mov_b32_e32 v9, v0
	v_mov_b32_e32 v10, v0
	v_mov_b32_e32 v11, v0
	v_mov_b32_e32 v12, v0
	v_mov_b32_e32 v13, v0
	v_mov_b32_e32 v14, v0
	v_mov_b32_e32 v15, v0
	v_mov_b32_e32 v24, v0
	v_mov_b32_e32 v25, v0
	v_mov_b32_e32 v26, v0
	v_mov_b32_e32 v27, v0
	v_mov_b32_e32 v28, v0
	v_mov_b32_e32 v29, v0
	v_mov_b32_e32 v30, v0
	v_mov_b32_e32 v31, v0
	v_mov_b32_e32 v40, v0
	v_mov_b32_e32 v41, v0
	v_mov_b32_e32 v42, v0
	v_mov_b32_e32 v43, v0
	v_mov_b32_e32 v44, v0
	v_mov_b32_e32 v45, v0
	v_mov_b32_e32 v46, v0
	v_mov_b32_e32 v47, v0
	v_mov_b32_e32 v56, v0
	v_mov_b32_e32 v57, v0
	v_mov_b32_e32 v58, v0
	v_mov_b32_e32 v59, v0
	v_mov_b32_e32 v60, v0
	v_mov_b32_e32 v61, v0
	v_mov_b32_e32 v62, v0
	v_mov_b32_e32 v63, v0
	v_mov_b32_e32 v64, v0
	v_mov_b32_e32 v65, v0
	v_mov_b32_e32 v66, v0
	v_mov_b32_e32 v67, v0
	v_mov_b32_e32 v68, v0
	v_mov_b32_e32 v69, v0
	v_mov_b32_e32 v70, v0
	v_mov_b32_e32 v71, v0
	v_mov_b32_e32 v80, v0
	v_mov_b32_e32 v81, v0
	v_mov_b32_e32 v82, v0
	v_mov_b32_e32 v83, v0
	v_mov_b32_e32 v84, v0
	v_mov_b32_e32 v85, v0
	v_mov_b32_e32 v86, v0
	v_mov_b32_e32 v87, v0
	v_mov_b32_e32 v96, v0
	v_mov_b32_e32 v97, v0
	v_mov_b32_e32 v98, v0
	v_mov_b32_e32 v99, v0
	v_mov_b32_e32 v100, v0
	v_mov_b32_e32 v101, v0
	v_mov_b32_e32 v102, v0
	v_mov_b32_e32 v103, v0
	v_mov_b32_e32 v104, v0
	v_mov_b32_e32 v105, v0
	v_mov_b32_e32 v106, v0
	v_mov_b32_e32 v107, v0
	v_mov_b32_e32 v108, v0
	v_mov_b32_e32 v109, v0
	v_mov_b32_e32 v110, v0
	v_mov_b32_e32 v111, v0
	v_mov_b32_e32 v72, v0
	v_mov_b32_e32 v73, v0
	v_mov_b32_e32 v74, v0
	v_mov_b32_e32 v75, v0
	v_mov_b32_e32 v76, v0
	v_mov_b32_e32 v77, v0
	v_mov_b32_e32 v78, v0
	v_mov_b32_e32 v79, v0
	v_mov_b32_e32 v88, v0
	v_mov_b32_e32 v89, v0
	v_mov_b32_e32 v90, v0
	v_mov_b32_e32 v91, v0
	v_mov_b32_e32 v92, v0
	v_mov_b32_e32 v93, v0
	v_mov_b32_e32 v94, v0
	v_mov_b32_e32 v95, v0
	v_mov_b32_e32 v112, v0
	v_mov_b32_e32 v113, v0
	v_mov_b32_e32 v114, v0
	v_mov_b32_e32 v115, v0
	v_mov_b32_e32 v116, v0
	v_mov_b32_e32 v117, v0
	v_mov_b32_e32 v118, v0
	v_mov_b32_e32 v119, v0
	v_mov_b32_e32 v120, v0
	v_mov_b32_e32 v121, v0
	v_mov_b32_e32 v122, v0
	v_mov_b32_e32 v123, v0
	v_mov_b32_e32 v124, v0
	v_mov_b32_e32 v125, v0
	v_mov_b32_e32 v126, v0
	v_mov_b32_e32 v127, v0
	s_nop 0

.LBB0_883:
	s_or_b64 exec, exec, s[0:1]
	s_waitcnt lgkmcnt(0)
	s_barrier
	s_nop 0

.LBB0_1076:
	s_ashr_i32 s17, s16, 31
	s_lshl_b64 s[18:19], s[16:17], 19
	s_add_u32 s18, s36, s18
	s_addc_u32 s19, s37, s19
	s_and_b64 s[20:21], s[2:3], exec
	s_cselect_b32 s17, s19, s29
	s_cselect_b32 s33, s18, s28
	s_ashr_i32 s15, s14, 31
	s_lshl_b64 s[20:21], s[14:15], 19
	s_add_u32 s20, s38, s20
	s_addc_u32 s21, s39, s21
	s_and_b64 s[34:35], s[2:3], exec
	s_cselect_b32 s15, s21, s31
	s_cselect_b32 s55, s20, s30
	s_add_u32 s28, s28, 0x40080
	s_addc_u32 s29, s29, 0
	s_add_u32 s56, s30, 0x100
	v_mov_b32_e32 v0, 0
	s_addc_u32 s57, s31, 0
	s_mov_b32 s58, -2
	v_mov_b32_e32 v1, v0
	v_mov_b32_e32 v2, v0
	v_mov_b32_e32 v3, v0
	v_mov_b32_e32 v4, v0
	v_mov_b32_e32 v5, v0
	v_mov_b32_e32 v6, v0
	v_mov_b32_e32 v7, v0
	v_mov_b32_e32 v16, v0
	v_mov_b32_e32 v17, v0
	v_mov_b32_e32 v18, v0
	v_mov_b32_e32 v19, v0
	v_mov_b32_e32 v20, v0
	v_mov_b32_e32 v21, v0
	v_mov_b32_e32 v22, v0
	v_mov_b32_e32 v23, v0
	v_mov_b32_e32 v32, v0
	v_mov_b32_e32 v33, v0
	v_mov_b32_e32 v34, v0
	v_mov_b32_e32 v35, v0
	v_mov_b32_e32 v36, v0
	v_mov_b32_e32 v37, v0
	v_mov_b32_e32 v38, v0
	v_mov_b32_e32 v39, v0
	v_mov_b32_e32 v48, v0
	v_mov_b32_e32 v49, v0
	v_mov_b32_e32 v50, v0
	v_mov_b32_e32 v51, v0
	v_mov_b32_e32 v52, v0
	v_mov_b32_e32 v53, v0
	v_mov_b32_e32 v54, v0
	v_mov_b32_e32 v55, v0
	v_mov_b32_e32 v8, v0
	v_mov_b32_e32 v9, v0
	v_mov_b32_e32 v10, v0
	v_mov_b32_e32 v11, v0
	v_mov_b32_e32 v12, v0
	v_mov_b32_e32 v13, v0
	v_mov_b32_e32 v14, v0
	v_mov_b32_e32 v15, v0
	v_mov_b32_e32 v24, v0
	v_mov_b32_e32 v25, v0
	v_mov_b32_e32 v26, v0
	v_mov_b32_e32 v27, v0
	v_mov_b32_e32 v28, v0
	v_mov_b32_e32 v29, v0
	v_mov_b32_e32 v30, v0
	v_mov_b32_e32 v31, v0
	v_mov_b32_e32 v40, v0
	v_mov_b32_e32 v41, v0
	v_mov_b32_e32 v42, v0
	v_mov_b32_e32 v43, v0
	v_mov_b32_e32 v44, v0
	v_mov_b32_e32 v45, v0
	v_mov_b32_e32 v46, v0
	v_mov_b32_e32 v47, v0
	v_mov_b32_e32 v56, v0
	v_mov_b32_e32 v57, v0
	v_mov_b32_e32 v58, v0
	v_mov_b32_e32 v59, v0
	v_mov_b32_e32 v72, v0
	v_mov_b32_e32 v73, v0
	v_mov_b32_e32 v74, v0
	v_mov_b32_e32 v75, v0
	v_mov_b32_e32 v80, v0
	v_mov_b32_e32 v81, v0
	v_mov_b32_e32 v82, v0
	v_mov_b32_e32 v83, v0
	v_mov_b32_e32 v84, v0
	v_mov_b32_e32 v85, v0
	v_mov_b32_e32 v86, v0
	v_mov_b32_e32 v87, v0
	v_mov_b32_e32 v96, v0
	v_mov_b32_e32 v97, v0
	v_mov_b32_e32 v98, v0
	v_mov_b32_e32 v99, v0
	v_mov_b32_e32 v100, v0
	v_mov_b32_e32 v101, v0
	v_mov_b32_e32 v102, v0
	v_mov_b32_e32 v103, v0
	v_mov_b32_e32 v112, v0
	v_mov_b32_e32 v113, v0
	v_mov_b32_e32 v114, v0
	v_mov_b32_e32 v115, v0
	v_mov_b32_e32 v116, v0
	v_mov_b32_e32 v117, v0
	v_mov_b32_e32 v118, v0
	v_mov_b32_e32 v119, v0
	v_mov_b32_e32 v128, v0
	v_mov_b32_e32 v129, v0
	v_mov_b32_e32 v130, v0
	v_mov_b32_e32 v131, v0
	v_mov_b32_e32 v132, v0
	v_mov_b32_e32 v133, v0
	v_mov_b32_e32 v134, v0
	v_mov_b32_e32 v135, v0
	v_mov_b32_e32 v88, v0
	v_mov_b32_e32 v89, v0
	v_mov_b32_e32 v90, v0
	v_mov_b32_e32 v91, v0
	v_mov_b32_e32 v92, v0
	v_mov_b32_e32 v93, v0
	v_mov_b32_e32 v94, v0
	v_mov_b32_e32 v95, v0
	v_mov_b32_e32 v104, v0
	v_mov_b32_e32 v105, v0
	v_mov_b32_e32 v106, v0
	v_mov_b32_e32 v107, v0
	v_mov_b32_e32 v108, v0
	v_mov_b32_e32 v109, v0
	v_mov_b32_e32 v110, v0
	v_mov_b32_e32 v111, v0
	v_mov_b32_e32 v120, v0
	v_mov_b32_e32 v121, v0
	v_mov_b32_e32 v122, v0
	v_mov_b32_e32 v123, v0
	v_mov_b32_e32 v124, v0
	v_mov_b32_e32 v125, v0
	v_mov_b32_e32 v126, v0
	v_mov_b32_e32 v127, v0
	v_mov_b32_e32 v136, v0
	v_mov_b32_e32 v137, v0
	v_mov_b32_e32 v138, v0
	v_mov_b32_e32 v139, v0
	v_mov_b32_e32 v140, v0
	v_mov_b32_e32 v141, v0
	v_mov_b32_e32 v142, v0
	v_mov_b32_e32 v143, v0
	s_nop 0

.LBB0_1307:
	s_ashr_i32 s15, s14, 31
	s_lshl_b64 s[16:17], s[14:15], 19
	s_add_u32 s16, s30, s16
	s_addc_u32 s17, s31, s17
	s_and_b64 s[18:19], s[2:3], exec
	s_cselect_b32 s15, s17, s23
	s_cselect_b32 s50, s16, s22
	s_ashr_i32 s13, s12, 31
	s_lshl_b64 s[18:19], s[12:13], 19
	s_add_u32 s18, s34, s18
	s_addc_u32 s19, s35, s19
	s_and_b64 s[28:29], s[2:3], exec
	s_cselect_b32 s13, s19, s25
	s_cselect_b32 s51, s18, s24
	s_add_u32 s22, s22, 0x40080
	s_addc_u32 s23, s23, 0
	s_add_u32 s52, s24, 0x100
	v_mov_b32_e32 v0, 0
	s_addc_u32 s53, s25, 0
	s_mov_b32 s54, -2
	v_mov_b32_e32 v1, v0
	v_mov_b32_e32 v2, v0
	v_mov_b32_e32 v3, v0
	v_mov_b32_e32 v8, v0
	v_mov_b32_e32 v9, v0
	v_mov_b32_e32 v10, v0
	v_mov_b32_e32 v11, v0
	v_mov_b32_e32 v16, v0
	v_mov_b32_e32 v17, v0
	v_mov_b32_e32 v18, v0
	v_mov_b32_e32 v19, v0
	v_mov_b32_e32 v24, v0
	v_mov_b32_e32 v25, v0
	v_mov_b32_e32 v26, v0
	v_mov_b32_e32 v27, v0
	v_mov_b32_e32 v32, v0
	v_mov_b32_e32 v33, v0
	v_mov_b32_e32 v34, v0
	v_mov_b32_e32 v35, v0
	v_mov_b32_e32 v40, v0
	v_mov_b32_e32 v41, v0
	v_mov_b32_e32 v42, v0
	v_mov_b32_e32 v43, v0
	v_mov_b32_e32 v48, v0
	v_mov_b32_e32 v49, v0
	v_mov_b32_e32 v50, v0
	v_mov_b32_e32 v51, v0
	v_mov_b32_e32 v56, v0
	v_mov_b32_e32 v57, v0
	v_mov_b32_e32 v58, v0
	v_mov_b32_e32 v59, v0
	v_mov_b32_e32 v4, v0
	v_mov_b32_e32 v5, v0
	v_mov_b32_e32 v6, v0
	v_mov_b32_e32 v7, v0
	v_mov_b32_e32 v12, v0
	v_mov_b32_e32 v13, v0
	v_mov_b32_e32 v14, v0
	v_mov_b32_e32 v15, v0
	v_mov_b32_e32 v20, v0
	v_mov_b32_e32 v21, v0
	v_mov_b32_e32 v22, v0
	v_mov_b32_e32 v23, v0
	v_mov_b32_e32 v28, v0
	v_mov_b32_e32 v29, v0
	v_mov_b32_e32 v30, v0
	v_mov_b32_e32 v31, v0
	v_mov_b32_e32 v36, v0
	v_mov_b32_e32 v37, v0
	v_mov_b32_e32 v38, v0
	v_mov_b32_e32 v39, v0
	v_mov_b32_e32 v44, v0
	v_mov_b32_e32 v45, v0
	v_mov_b32_e32 v46, v0
	v_mov_b32_e32 v47, v0
	v_mov_b32_e32 v52, v0
	v_mov_b32_e32 v53, v0
	v_mov_b32_e32 v54, v0
	v_mov_b32_e32 v55, v0
	v_mov_b32_e32 v60, v0
	v_mov_b32_e32 v61, v0
	v_mov_b32_e32 v62, v0
	v_mov_b32_e32 v63, v0
	v_mov_b32_e32 v64, v0
	v_mov_b32_e32 v65, v0
	v_mov_b32_e32 v66, v0
	v_mov_b32_e32 v67, v0
	v_mov_b32_e32 v72, v0
	v_mov_b32_e32 v73, v0
	v_mov_b32_e32 v74, v0
	v_mov_b32_e32 v75, v0
	v_mov_b32_e32 v80, v0
	v_mov_b32_e32 v81, v0
	v_mov_b32_e32 v82, v0
	v_mov_b32_e32 v83, v0
	v_mov_b32_e32 v88, v0
	v_mov_b32_e32 v89, v0
	v_mov_b32_e32 v90, v0
	v_mov_b32_e32 v91, v0
	v_mov_b32_e32 v96, v0
	v_mov_b32_e32 v97, v0
	v_mov_b32_e32 v98, v0
	v_mov_b32_e32 v99, v0
	v_mov_b32_e32 v104, v0
	v_mov_b32_e32 v105, v0
	v_mov_b32_e32 v106, v0
	v_mov_b32_e32 v107, v0
	v_mov_b32_e32 v112, v0
	v_mov_b32_e32 v113, v0
	v_mov_b32_e32 v114, v0
	v_mov_b32_e32 v115, v0
	v_mov_b32_e32 v120, v0
	v_mov_b32_e32 v121, v0
	v_mov_b32_e32 v122, v0
	v_mov_b32_e32 v123, v0
	v_mov_b32_e32 v68, v0
	v_mov_b32_e32 v69, v0
	v_mov_b32_e32 v70, v0
	v_mov_b32_e32 v71, v0
	v_mov_b32_e32 v76, v0
	v_mov_b32_e32 v77, v0
	v_mov_b32_e32 v78, v0
	v_mov_b32_e32 v79, v0
	v_mov_b32_e32 v84, v0
	v_mov_b32_e32 v85, v0
	v_mov_b32_e32 v86, v0
	v_mov_b32_e32 v87, v0
	v_mov_b32_e32 v92, v0
	v_mov_b32_e32 v93, v0
	v_mov_b32_e32 v94, v0
	v_mov_b32_e32 v95, v0
	v_mov_b32_e32 v100, v0
	v_mov_b32_e32 v101, v0
	v_mov_b32_e32 v102, v0
	v_mov_b32_e32 v103, v0
	v_mov_b32_e32 v108, v0
	v_mov_b32_e32 v109, v0
	v_mov_b32_e32 v110, v0
	v_mov_b32_e32 v111, v0
	v_mov_b32_e32 v116, v0
	v_mov_b32_e32 v117, v0
	v_mov_b32_e32 v118, v0
	v_mov_b32_e32 v119, v0
	v_mov_b32_e32 v124, v0
	v_mov_b32_e32 v125, v0
	v_mov_b32_e32 v126, v0
	v_mov_b32_e32 v127, v0
	s_nop 0
